# gates->merge + merge->out barriers XCD-local; B-finalize remap keeps a compact 512-token window per XCD per step
# baseline (speedup 1.0000x reference)
.LBB0_582:
	s_or_b64 exec, exec, s[0:1]
	s_mov_b64 s[0:1], 0
	s_waitcnt lgkmcnt(0)
	s_barrier
	v_mov_b32_e32 v0, v197
	s_add_u32 s0, s96, s0
	s_addc_u32 s1, s97, s1
	s_and_b32 s2, s52, 7
	s_lshl_b32 s2, s2, 16
	s_lshr_b32 s3, s52, 3
	s_lshl_b32 s3, s3, 9
	s_add_i32 s2, s2, s3
	v_add_u32_e32 v66, s2, v0
	v_cmp_gt_i32_e32 vcc, s80, v66
	s_and_saveexec_b64 s[10:11], vcc
	s_cbranch_execz .LBB0_597
	s_add_u32 s12, s0, 0x7800000
	s_addc_u32 s13, s1, 0
	v_readlane_b32 s2, v253, 62
	s_add_u32 s14, s0, 0x10900000
	s_addc_u32 s15, s1, 0
	v_lshl_add_u32 v76, v0, 3, s2
	v_mov_b32_e32 v0, 0
	s_mov_b64 s[16:17], 0
	v_mov_b32_e32 v1, v0
	v_mov_b32_e32 v2, v0
	v_mov_b32_e32 v3, v0
	v_mov_b32_e32 v16, v0
	v_mov_b32_e32 v17, v0
	v_mov_b32_e32 v18, v0
	v_mov_b32_e32 v19, v0
	v_mov_b32_e32 v32, v0
	v_mov_b32_e32 v33, v0
	v_mov_b32_e32 v34, v0
	v_mov_b32_e32 v35, v0
	v_mov_b32_e32 v36, v0
	v_mov_b32_e32 v37, v0
	v_mov_b32_e32 v38, v0
	v_mov_b32_e32 v39, v0
	v_mov_b32_e32 v40, v0
	v_mov_b32_e32 v41, v0
	v_mov_b32_e32 v42, v0
	v_mov_b32_e32 v43, v0
	v_mov_b32_e32 v44, v0
	v_mov_b32_e32 v45, v0
	v_mov_b32_e32 v46, v0
	v_mov_b32_e32 v47, v0
	s_branch .LBB0_585

.LBB0_585:
	v_ashrrev_i32_e32 v60, 5, v66
	v_bfe_u32 v67, v66, 3, 2
	v_ashrrev_i32_e32 v61, 31, v60
	v_lshl_add_u64 v[48:49], v[60:61], 4, s[14:15]
	v_lshlrev_b32_e32 v194, 2, v67
	v_lshl_add_u64 v[48:49], v[48:49], 0, v[194:195]
	s_mov_b32 s2, 0x40000
	v_add_co_u32_e32 v50, vcc, s2, v48
	v_mov_b64_e32 v[54:55], s[12:13]
	v_and_b32_e32 v56, 56, v76
	v_addc_co_u32_e32 v51, vcc, 0, v49, vcc
	v_mad_i64_i32 v[54:55], s[2:3], v60, s99, v[54:55]
	v_lshlrev_b32_e32 v62, 7, v67
	v_mov_b32_e32 v63, v195
	v_add_co_u32_e32 v52, vcc, s80, v48
	v_lshl_add_u64 v[54:55], v[54:55], 0, v[62:63]
	v_lshlrev_b32_e32 v64, 1, v56
	v_mov_b32_e32 v65, v195
	v_lshlrev_b64 v[60:61], 11, v[60:61]
	v_addc_co_u32_e32 v53, vcc, 0, v49, vcc
	v_lshl_add_u64 v[56:57], v[54:55], 0, v[64:65]
	v_lshl_add_u64 v[72:73], s[0:1], 0, v[60:61]
	global_load_dword v89, v[48:49], off
	global_load_dword v88, v[50:51], off
	global_load_dword v87, v[52:53], off
	s_nop 0
	global_load_dwordx4 v[48:51], v[56:57], off
	global_load_dwordx4 v[52:55], v[56:57], off offset:512
	s_nop 0
	global_load_dwordx4 v[56:59], v[56:57], off offset:1024
	v_lshl_add_u64 v[60:61], v[72:73], 0, v[62:63]
	v_lshl_add_u64 v[60:61], v[60:61], 0, v[64:65]
	v_add_co_u32_e32 v60, vcc, 0x9000000, v60
	v_add_u32_e32 v86, 0x4000, v66
	s_nop 0
	v_addc_co_u32_e32 v61, vcc, 0, v61, vcc
	global_load_dwordx4 v[60:63], v[60:61], off offset:1024
	v_lshlrev_b32_e32 v67, 6, v67
	v_ashrrev_i32_e32 v70, 5, v86
	v_cmp_gt_i32_e64 s[8:9], s80, v86
	v_ashrrev_i32_e32 v71, 31, v70
	v_lshlrev_b32_e32 v74, 1, v67
	s_and_saveexec_b64 s[4:5], s[8:9]
	s_cbranch_execz .LBB0_587
	v_lshl_add_u64 v[0:1], v[70:71], 4, s[14:15]
	v_lshl_add_u64 v[0:1], v[0:1], 0, v[194:195]
	v_add_co_u32_e32 v2, vcc, 0x40000, v0
	s_waitcnt vmcnt(8)
	v_mov_b64_e32 v[6:7], s[12:13]
	v_addc_co_u32_e32 v3, vcc, 0, v1, vcc
	v_mad_i64_i32 v[6:7], s[2:3], v70, s99, v[6:7]
	v_mov_b32_e32 v75, v195
	v_add_co_u32_e32 v4, vcc, 0x80000, v0
	v_lshl_add_u64 v[6:7], v[6:7], 0, v[74:75]
	v_lshlrev_b64 v[20:21], 11, v[70:71]
	v_addc_co_u32_e32 v5, vcc, 0, v1, vcc
	v_lshl_add_u64 v[6:7], v[6:7], 0, v[64:65]
	v_lshl_add_u64 v[20:21], s[0:1], 0, v[20:21]
	global_load_dword v77, v[0:1], off
	global_load_dword v80, v[2:3], off
	global_load_dword v83, v[4:5], off
	s_nop 0
	global_load_dwordx4 v[0:3], v[6:7], off
	global_load_dwordx4 v[36:39], v[6:7], off offset:512
	s_nop 0
	global_load_dwordx4 v[4:7], v[6:7], off offset:1024
	v_lshl_add_u64 v[20:21], v[20:21], 0, v[74:75]
	v_lshl_add_u64 v[20:21], v[20:21], 0, v[64:65]
	v_add_co_u32_e32 v20, vcc, s79, v20
	s_nop 1
	v_addc_co_u32_e32 v21, vcc, 0, v21, vcc
	global_load_dwordx4 v[20:23], v[20:21], off offset:1024
.LBB0_587:
	s_or_b64 exec, exec, s[4:5]
	v_add_u32_e32 v65, 0x8000, v66
	v_ashrrev_i32_e32 v68, 5, v65
	v_cmp_gt_i32_e64 s[6:7], s80, v65
	v_ashrrev_i32_e32 v69, 31, v68
	s_and_saveexec_b64 s[4:5], s[6:7]
	s_cbranch_execz .LBB0_589
	v_lshl_add_u64 v[12:13], v[68:69], 4, s[14:15]
	v_lshl_add_u64 v[12:13], v[12:13], 0, v[194:195]
	v_add_co_u32_e32 v14, vcc, 0x40000, v12
	v_mov_b64_e32 v[18:19], s[12:13]
	s_nop 0
	v_addc_co_u32_e32 v15, vcc, 0, v13, vcc
	v_mad_i64_i32 v[18:19], s[2:3], v68, s99, v[18:19]
	v_mov_b32_e32 v75, v195
	v_add_co_u32_e32 v16, vcc, 0x80000, v12
	v_lshl_add_u64 v[18:19], v[18:19], 0, v[74:75]
	v_mov_b32_e32 v65, v195
	v_addc_co_u32_e32 v17, vcc, 0, v13, vcc
	v_lshl_add_u64 v[28:29], v[18:19], 0, v[64:65]
	global_load_dword v79, v[12:13], off
	global_load_dword v82, v[14:15], off
	global_load_dword v85, v[16:17], off
	s_nop 0
	global_load_dwordx4 v[16:19], v[28:29], off
	global_load_dwordx4 v[40:43], v[28:29], off offset:512
	global_load_dwordx4 v[12:15], v[28:29], off offset:1024
	v_lshlrev_b64 v[28:29], 11, v[68:69]
	v_lshl_add_u64 v[28:29], s[0:1], 0, v[28:29]
	v_lshl_add_u64 v[28:29], v[28:29], 0, v[74:75]
	v_lshl_add_u64 v[28:29], v[28:29], 0, v[64:65]
	v_add_co_u32_e32 v28, vcc, s79, v28
	s_nop 1
	v_addc_co_u32_e32 v29, vcc, 0, v29, vcc
	global_load_dwordx4 v[28:31], v[28:29], off offset:1024
.LBB0_589:
	s_or_b64 exec, exec, s[4:5]
	s_mov_b32 s2, 0xc000
	v_add_u32_e32 v65, s2, v66
	v_ashrrev_i32_e32 v66, 5, v65
	v_cmp_gt_i32_e64 s[4:5], s80, v65
	v_ashrrev_i32_e32 v67, 31, v66
	s_and_saveexec_b64 s[18:19], s[4:5]
	s_cbranch_execz .LBB0_591
	v_lshl_add_u64 v[8:9], v[66:67], 4, s[14:15]
	v_lshl_add_u64 v[8:9], v[8:9], 0, v[194:195]
	v_add_co_u32_e32 v10, vcc, 0x40000, v8
	v_mov_b64_e32 v[26:27], s[12:13]
	s_nop 0
	v_addc_co_u32_e32 v11, vcc, 0, v9, vcc
	v_add_co_u32_e32 v24, vcc, 0x80000, v8
	v_mad_i64_i32 v[26:27], s[2:3], v66, s99, v[26:27]
	v_mov_b32_e32 v75, v195
	v_addc_co_u32_e32 v25, vcc, 0, v9, vcc
	v_lshl_add_u64 v[26:27], v[26:27], 0, v[74:75]
	v_mov_b32_e32 v65, v195
	v_lshl_add_u64 v[26:27], v[26:27], 0, v[64:65]
	global_load_dword v78, v[8:9], off
	global_load_dword v81, v[10:11], off
	global_load_dword v84, v[24:25], off
	global_load_dwordx4 v[32:35], v[26:27], off
	global_load_dwordx4 v[44:47], v[26:27], off offset:512
	s_nop 0
	global_load_dwordx4 v[8:11], v[26:27], off offset:1024
	v_lshlrev_b64 v[24:25], 11, v[66:67]
	v_lshl_add_u64 v[24:25], s[0:1], 0, v[24:25]
	v_lshl_add_u64 v[24:25], v[24:25], 0, v[74:75]
	v_lshl_add_u64 v[24:25], v[24:25], 0, v[64:65]
	v_add_co_u32_e32 v24, vcc, s79, v24
	s_nop 1
	v_addc_co_u32_e32 v25, vcc, 0, v25, vcc
	global_load_dwordx4 v[24:27], v[24:25], off offset:1024
